# K-loop heads of the eight GEMM phases aligned to 64 bytes
# baseline (speedup 1.0000x reference)
;     __device__ bool next(int i, pg8::Unit& u) const { const int cnt = (nwg - c + G - 1) / G; if (i >= reps * cnt) return false; return pg8::StaticOrder::next(i % cnt, u); }
; template <class Epi, class Sched, bool ALIGN_EPI = false, bool SP2 = false>
; __device__ __forceinline__ void gemm_phase(PG8_LAS unsigned char* lds, const Gemm g, const Sched& S, const Epi& E) {
;     ...
;         const bool has_next = S.next(ui + 1, nxt);
;         const char* nA = has_next ? (const char*)g.A + (size_t)nxt.pm * tstep : cA; const char* nB = has_next ? (const char*)g.Bt + (size_t)nxt.pn * tstep : cB;
;         for (int t = 0; t < nt; t += 2) {
;             const bool last = (t == nt - 2);
;             const char* a1 = cA + (size_t)(t + 1) * kstep;
;             const char* a2 = last ? nA : cA + (size_t)(t + 2) * kstep; const char* b2 = last ? nB : cB + (size_t)(t + 2) * kstep;
;             const char* a3 = a2 + kstep; const char* b3 = b2 + kstep;
;     ...
; #pragma unroll
;         for (int a = 0; a < 2; ++a)
; #pragma unroll
;             for (int b = 0; b < 2; ++b)
; #pragma unroll
;                 for (int m = 0; m < 4; ++m)
; #pragma unroll
;                     for (int n = 0; n < 2; ++n) acc[a][b][m][n] = (f32x4){0.f, 0.f, 0.f, 0.f};
.LBB0_128:
	s_ashr_i32 s25, s24, 31
	s_lshl_b64 s[28:29], s[24:25], 20
	v_readlane_b32 s30, v254, 51
	v_readlane_b32 s31, v254, 52
	s_add_u32 s28, s30, s28
	s_addc_u32 s29, s31, s29
	s_and_b64 s[30:31], s[26:27], exec
	s_cselect_b32 s25, s29, s9
	s_cselect_b32 s35, s28, s8
	s_ashr_i32 s23, s22, 31
	s_lshl_b64 s[30:31], s[22:23], 20
	s_add_u32 s30, s94, s30
	s_addc_u32 s31, s95, s31
	s_and_b64 s[46:47], s[26:27], exec
	s_cselect_b32 s23, s31, s45
	s_cselect_b32 s43, s30, s44
	s_add_u32 s8, s8, 0x80080
	s_addc_u32 s9, s9, 0
	s_add_u32 s48, s44, 0x100
	v_mov_b64_e32 v[0:1], 0
	v_mov_b64_e32 v[2:3], 0
	v_mov_b64_e32 v[4:5], 0
	v_mov_b64_e32 v[6:7], 0
	v_mov_b64_e32 v[8:9], 0
	v_mov_b64_e32 v[10:11], 0
	v_mov_b64_e32 v[12:13], 0
	v_mov_b64_e32 v[14:15], 0
	v_mov_b64_e32 v[16:17], 0
	v_mov_b64_e32 v[18:19], 0
	v_mov_b64_e32 v[20:21], 0
	v_mov_b64_e32 v[22:23], 0
	v_mov_b64_e32 v[24:25], 0
	v_mov_b64_e32 v[26:27], 0
	v_mov_b64_e32 v[28:29], 0
	v_mov_b64_e32 v[30:31], 0
	v_mov_b64_e32 v[32:33], 0
	v_mov_b64_e32 v[34:35], 0
	v_mov_b64_e32 v[36:37], 0
	v_mov_b64_e32 v[38:39], 0
	v_mov_b64_e32 v[40:41], 0
	v_mov_b64_e32 v[42:43], 0
	v_mov_b64_e32 v[44:45], 0
	v_mov_b64_e32 v[46:47], 0
	v_mov_b64_e32 v[48:49], 0
	v_mov_b64_e32 v[50:51], 0
	v_mov_b64_e32 v[52:53], 0
	v_mov_b64_e32 v[54:55], 0
	v_mov_b64_e32 v[56:57], 0
	v_mov_b64_e32 v[58:59], 0
	v_mov_b64_e32 v[60:61], 0
	v_mov_b64_e32 v[62:63], 0
	v_mov_b64_e32 v[64:65], 0
	v_mov_b64_e32 v[66:67], 0
	v_mov_b64_e32 v[68:69], 0
	v_mov_b64_e32 v[70:71], 0
	v_mov_b64_e32 v[72:73], 0
	v_mov_b64_e32 v[74:75], 0
	v_mov_b64_e32 v[76:77], 0
	v_mov_b64_e32 v[78:79], 0
	v_mov_b64_e32 v[80:81], 0
	v_mov_b64_e32 v[82:83], 0
	v_mov_b64_e32 v[84:85], 0
	v_mov_b64_e32 v[86:87], 0
	v_mov_b64_e32 v[88:89], 0
	v_mov_b64_e32 v[90:91], 0
	v_mov_b64_e32 v[92:93], 0
	v_mov_b64_e32 v[94:95], 0
	v_mov_b64_e32 v[108:109], 0
	v_mov_b64_e32 v[110:111], 0
	v_mov_b64_e32 v[116:117], 0
	v_mov_b64_e32 v[118:119], 0
	v_mov_b64_e32 v[120:121], 0
	v_mov_b64_e32 v[122:123], 0
	v_mov_b64_e32 v[124:125], 0
	v_mov_b64_e32 v[126:127], 0
	v_mov_b64_e32 v[128:129], 0
	v_mov_b64_e32 v[130:131], 0
	v_mov_b64_e32 v[132:133], 0
	v_mov_b64_e32 v[134:135], 0
	v_mov_b64_e32 v[136:137], 0
	v_mov_b64_e32 v[138:139], 0
	v_mov_b64_e32 v[140:141], 0
	v_mov_b64_e32 v[142:143], 0
	s_addc_u32 s49, s45, 0
	s_mov_b32 s54, -2
	s_waitcnt lgkmcnt(0)
	.p2align	6

;     __device__ bool next(int i, pg8::Unit& u) const { const int cnt = (nwg - c + G - 1) / G; if (i >= reps * cnt) return false; return pg8::StaticOrder::next(i % cnt, u); }
; template <class Epi, class Sched, bool ALIGN_EPI = false, bool SP2 = false>
; __device__ __forceinline__ void gemm_phase(PG8_LAS unsigned char* lds, const Gemm g, const Sched& S, const Epi& E) {
;     ...
;         const bool has_next = S.next(ui + 1, nxt);
;         const char* nA = has_next ? (const char*)g.A + (size_t)nxt.pm * tstep : cA; const char* nB = has_next ? (const char*)g.Bt + (size_t)nxt.pn * tstep : cB;
;         for (int t = 0; t < nt; t += 2) {
;             const bool last = (t == nt - 2);
;             const char* a1 = cA + (size_t)(t + 1) * kstep;
;             const char* a2 = last ? nA : cA + (size_t)(t + 2) * kstep; const char* b2 = last ? nB : cB + (size_t)(t + 2) * kstep;
;             const char* a3 = a2 + kstep; const char* b3 = b2 + kstep;
;     ...
; #pragma unroll
;         for (int a = 0; a < 2; ++a)
; #pragma unroll
;             for (int b = 0; b < 2; ++b)
; #pragma unroll
;                 for (int m = 0; m < 4; ++m)
; #pragma unroll
;                     for (int n = 0; n < 2; ++n) acc[a][b][m][n] = (f32x4){0.f, 0.f, 0.f, 0.f};
.LBB0_306:
	s_ashr_i32 s21, s20, 31
	s_lshl_b64 s[22:23], s[20:21], 20
	s_add_u32 s22, s60, s22
	s_addc_u32 s23, s61, s23
	s_and_b64 s[24:25], s[4:5], exec
	s_cselect_b32 s7, s23, s27
	s_cselect_b32 s21, s22, s26
	s_ashr_i32 s19, s18, 31
	s_lshl_b64 s[24:25], s[18:19], 20
	s_add_u32 s24, s68, s24
	s_addc_u32 s25, s69, s25
	s_and_b64 s[30:31], s[4:5], exec
	s_cselect_b32 s19, s25, s29
	s_cselect_b32 s33, s24, s28
	s_add_u32 s26, s26, 0x80080
	s_addc_u32 s27, s27, 0
	s_add_u32 s48, s28, 0x100
	v_mov_b64_e32 v[0:1], 0
	v_mov_b64_e32 v[2:3], 0
	v_mov_b64_e32 v[4:5], 0
	v_mov_b64_e32 v[6:7], 0
	v_mov_b64_e32 v[8:9], 0
	v_mov_b64_e32 v[10:11], 0
	v_mov_b64_e32 v[12:13], 0
	v_mov_b64_e32 v[14:15], 0
	v_mov_b64_e32 v[16:17], 0
	v_mov_b64_e32 v[18:19], 0
	v_mov_b64_e32 v[20:21], 0
	v_mov_b64_e32 v[22:23], 0
	v_mov_b64_e32 v[24:25], 0
	v_mov_b64_e32 v[26:27], 0
	v_mov_b64_e32 v[28:29], 0
	v_mov_b64_e32 v[30:31], 0
	v_mov_b64_e32 v[32:33], 0
	v_mov_b64_e32 v[34:35], 0
	v_mov_b64_e32 v[36:37], 0
	v_mov_b64_e32 v[38:39], 0
	v_mov_b64_e32 v[40:41], 0
	v_mov_b64_e32 v[42:43], 0
	v_mov_b64_e32 v[44:45], 0
	v_mov_b64_e32 v[46:47], 0
	v_mov_b64_e32 v[48:49], 0
	v_mov_b64_e32 v[50:51], 0
	v_mov_b64_e32 v[52:53], 0
	v_mov_b64_e32 v[54:55], 0
	v_mov_b64_e32 v[56:57], 0
	v_mov_b64_e32 v[58:59], 0
	v_mov_b64_e32 v[60:61], 0
	v_mov_b64_e32 v[62:63], 0
	v_mov_b64_e32 v[64:65], 0
	v_mov_b64_e32 v[66:67], 0
	v_mov_b64_e32 v[68:69], 0
	v_mov_b64_e32 v[70:71], 0
	v_mov_b64_e32 v[72:73], 0
	v_mov_b64_e32 v[74:75], 0
	v_mov_b64_e32 v[76:77], 0
	v_mov_b64_e32 v[78:79], 0
	v_mov_b64_e32 v[80:81], 0
	v_mov_b64_e32 v[82:83], 0
	v_mov_b64_e32 v[84:85], 0
	v_mov_b64_e32 v[86:87], 0
	v_mov_b64_e32 v[88:89], 0
	v_mov_b64_e32 v[90:91], 0
	v_mov_b64_e32 v[92:93], 0
	v_mov_b64_e32 v[94:95], 0
	v_mov_b64_e32 v[96:97], 0
	v_mov_b64_e32 v[98:99], 0
	v_mov_b64_e32 v[100:101], 0
	v_mov_b64_e32 v[102:103], 0
	v_mov_b64_e32 v[104:105], 0
	v_mov_b64_e32 v[106:107], 0
	v_mov_b64_e32 v[108:109], 0
	v_mov_b64_e32 v[110:111], 0
	v_mov_b64_e32 v[112:113], 0
	v_mov_b64_e32 v[114:115], 0
	v_mov_b64_e32 v[116:117], 0
	v_mov_b64_e32 v[118:119], 0
	v_mov_b64_e32 v[120:121], 0
	v_mov_b64_e32 v[122:123], 0
	v_mov_b64_e32 v[124:125], 0
	v_mov_b64_e32 v[126:127], 0
	s_addc_u32 s49, s29, 0
	s_mov_b32 s50, -2
	s_waitcnt lgkmcnt(0)
	s_waitcnt lgkmcnt(0)
	.p2align	6

;     __device__ bool next(int i, pg8::Unit& u) const { const int cnt = (nwg - c + G - 1) / G; if (i >= reps * cnt) return false; return pg8::StaticOrder::next(i % cnt, u); }
; template <class Epi, class Sched, bool ALIGN_EPI = false, bool SP2 = false>
; __device__ __forceinline__ void gemm_phase(PG8_LAS unsigned char* lds, const Gemm g, const Sched& S, const Epi& E) {
;     ...
;         const bool has_next = S.next(ui + 1, nxt);
;         const char* nA = has_next ? (const char*)g.A + (size_t)nxt.pm * tstep : cA; const char* nB = has_next ? (const char*)g.Bt + (size_t)nxt.pn * tstep : cB;
;         for (int t = 0; t < nt; t += 2) {
;             const bool last = (t == nt - 2);
;             const char* a1 = cA + (size_t)(t + 1) * kstep;
;             const char* a2 = last ? nA : cA + (size_t)(t + 2) * kstep; const char* b2 = last ? nB : cB + (size_t)(t + 2) * kstep;
;             const char* a3 = a2 + kstep; const char* b3 = b2 + kstep;
;     ...
; #pragma unroll
;         for (int a = 0; a < 2; ++a)
; #pragma unroll
;             for (int b = 0; b < 2; ++b)
; #pragma unroll
;                 for (int m = 0; m < 4; ++m)
; #pragma unroll
;                     for (int n = 0; n < 2; ++n) acc[a][b][m][n] = (f32x4){0.f, 0.f, 0.f, 0.f};
.LBB0_490:
	s_ashr_i32 s21, s20, 31
	s_lshl_b64 s[0:1], s[20:21], 20
	v_readlane_b32 s24, v254, 51
	v_readlane_b32 s25, v254, 52
	s_add_u32 s24, s24, s0
	s_addc_u32 s25, s25, s1
	s_and_b64 s[0:1], s[22:23], exec
	s_cselect_b32 s5, s25, s31
	s_cselect_b32 s21, s24, s30
	s_ashr_i32 s19, s18, 31
	s_lshl_b64 s[0:1], s[18:19], 20
	v_readlane_b32 s26, v254, 22
	v_readlane_b32 s27, v254, 23
	s_add_u32 s26, s26, s0
	s_addc_u32 s27, s27, s1
	s_and_b64 s[0:1], s[22:23], exec
	s_cselect_b32 s19, s27, s29
	s_cselect_b32 s33, s26, s28
	s_add_u32 s0, s30, 0x80080
	s_addc_u32 s1, s31, 0
	s_add_u32 s44, s28, 0x100
	v_mov_b64_e32 v[0:1], 0
	v_mov_b64_e32 v[2:3], 0
	v_mov_b64_e32 v[4:5], 0
	v_mov_b64_e32 v[6:7], 0
	v_mov_b64_e32 v[8:9], 0
	v_mov_b64_e32 v[10:11], 0
	v_mov_b64_e32 v[12:13], 0
	v_mov_b64_e32 v[14:15], 0
	v_mov_b64_e32 v[16:17], 0
	v_mov_b64_e32 v[18:19], 0
	v_mov_b64_e32 v[20:21], 0
	v_mov_b64_e32 v[22:23], 0
	v_mov_b64_e32 v[24:25], 0
	v_mov_b64_e32 v[26:27], 0
	v_mov_b64_e32 v[28:29], 0
	v_mov_b64_e32 v[30:31], 0
	v_mov_b64_e32 v[32:33], 0
	v_mov_b64_e32 v[34:35], 0
	v_mov_b64_e32 v[36:37], 0
	v_mov_b64_e32 v[38:39], 0
	v_mov_b64_e32 v[40:41], 0
	v_mov_b64_e32 v[42:43], 0
	v_mov_b64_e32 v[44:45], 0
	v_mov_b64_e32 v[46:47], 0
	v_mov_b64_e32 v[48:49], 0
	v_mov_b64_e32 v[50:51], 0
	v_mov_b64_e32 v[52:53], 0
	v_mov_b64_e32 v[54:55], 0
	v_mov_b64_e32 v[56:57], 0
	v_mov_b64_e32 v[58:59], 0
	v_mov_b64_e32 v[60:61], 0
	v_mov_b64_e32 v[62:63], 0
	v_mov_b64_e32 v[64:65], 0
	v_mov_b64_e32 v[66:67], 0
	v_mov_b64_e32 v[68:69], 0
	v_mov_b64_e32 v[70:71], 0
	v_mov_b64_e32 v[72:73], 0
	v_mov_b64_e32 v[74:75], 0
	v_mov_b64_e32 v[76:77], 0
	v_mov_b64_e32 v[78:79], 0
	v_mov_b64_e32 v[80:81], 0
	v_mov_b64_e32 v[82:83], 0
	v_mov_b64_e32 v[84:85], 0
	v_mov_b64_e32 v[86:87], 0
	v_mov_b64_e32 v[88:89], 0
	v_mov_b64_e32 v[90:91], 0
	v_mov_b64_e32 v[92:93], 0
	v_mov_b64_e32 v[94:95], 0
	v_mov_b64_e32 v[96:97], 0
	v_mov_b64_e32 v[98:99], 0
	v_mov_b64_e32 v[100:101], 0
	v_mov_b64_e32 v[102:103], 0
	v_mov_b64_e32 v[104:105], 0
	v_mov_b64_e32 v[106:107], 0
	v_mov_b64_e32 v[108:109], 0
	v_mov_b64_e32 v[110:111], 0
	v_mov_b64_e32 v[112:113], 0
	v_mov_b64_e32 v[114:115], 0
	v_mov_b64_e32 v[116:117], 0
	v_mov_b64_e32 v[118:119], 0
	v_mov_b64_e32 v[120:121], 0
	v_mov_b64_e32 v[122:123], 0
	v_mov_b64_e32 v[124:125], 0
	v_mov_b64_e32 v[126:127], 0
	s_addc_u32 s45, s29, 0
	s_mov_b32 s48, -2
	.p2align	6

;     __device__ bool next(int i, pg8::Unit& u) const { const int cnt = (nwg - c + G - 1) / G; if (i >= reps * cnt) return false; return pg8::StaticOrder::next(i % cnt, u); }
; template <class Epi, class Sched, bool ALIGN_EPI = false, bool SP2 = false>
; __device__ __forceinline__ void gemm_phase(PG8_LAS unsigned char* lds, const Gemm g, const Sched& S, const Epi& E) {
;     ...
;         const bool has_next = S.next(ui + 1, nxt);
;         const char* nA = has_next ? (const char*)g.A + (size_t)nxt.pm * tstep : cA; const char* nB = has_next ? (const char*)g.Bt + (size_t)nxt.pn * tstep : cB;
;         for (int t = 0; t < nt; t += 2) {
;             const bool last = (t == nt - 2);
;             const char* a1 = cA + (size_t)(t + 1) * kstep;
;             const char* a2 = last ? nA : cA + (size_t)(t + 2) * kstep; const char* b2 = last ? nB : cB + (size_t)(t + 2) * kstep;
;             const char* a3 = a2 + kstep; const char* b3 = b2 + kstep;
;     ...
; #pragma unroll
;         for (int a = 0; a < 2; ++a)
; #pragma unroll
;             for (int b = 0; b < 2; ++b)
; #pragma unroll
;                 for (int m = 0; m < 4; ++m)
; #pragma unroll
;                     for (int n = 0; n < 2; ++n) acc[a][b][m][n] = (f32x4){0.f, 0.f, 0.f, 0.f};
.LBB0_762:
	s_ashr_i32 s21, s20, 31
	s_lshl_b64 s[22:23], s[20:21], 21
	s_add_u32 s22, s60, s22
	s_addc_u32 s23, s61, s23
	s_and_b64 s[24:25], s[4:5], exec
	s_cselect_b32 s7, s23, s27
	s_cselect_b32 s21, s22, s26
	s_ashr_i32 s19, s18, 31
	s_lshl_b64 s[24:25], s[18:19], 21
	v_readlane_b32 s30, v254, 32
	v_readlane_b32 s31, v254, 33
	s_add_u32 s24, s30, s24
	s_addc_u32 s25, s31, s25
	s_and_b64 s[30:31], s[4:5], exec
	s_cselect_b32 s19, s25, s29
	s_cselect_b32 s48, s24, s28
	s_add_u32 s26, s26, 0x100080
	s_addc_u32 s27, s27, 0
	s_add_u32 s49, s28, 0x100
	v_mov_b64_e32 v[0:1], 0
	v_mov_b64_e32 v[2:3], 0
	v_mov_b64_e32 v[4:5], 0
	v_mov_b64_e32 v[6:7], 0
	v_mov_b64_e32 v[8:9], 0
	v_mov_b64_e32 v[10:11], 0
	v_mov_b64_e32 v[12:13], 0
	v_mov_b64_e32 v[14:15], 0
	v_mov_b64_e32 v[16:17], 0
	v_mov_b64_e32 v[18:19], 0
	v_mov_b64_e32 v[20:21], 0
	v_mov_b64_e32 v[22:23], 0
	v_mov_b64_e32 v[24:25], 0
	v_mov_b64_e32 v[26:27], 0
	v_mov_b64_e32 v[28:29], 0
	v_mov_b64_e32 v[30:31], 0
	v_mov_b64_e32 v[32:33], 0
	v_mov_b64_e32 v[34:35], 0
	v_mov_b64_e32 v[36:37], 0
	v_mov_b64_e32 v[38:39], 0
	v_mov_b64_e32 v[40:41], 0
	v_mov_b64_e32 v[42:43], 0
	v_mov_b64_e32 v[44:45], 0
	v_mov_b64_e32 v[46:47], 0
	v_mov_b64_e32 v[48:49], 0
	v_mov_b64_e32 v[50:51], 0
	v_mov_b64_e32 v[52:53], 0
	v_mov_b64_e32 v[54:55], 0
	v_mov_b64_e32 v[56:57], 0
	v_mov_b64_e32 v[58:59], 0
	v_mov_b64_e32 v[60:61], 0
	v_mov_b64_e32 v[62:63], 0
	v_mov_b64_e32 v[64:65], 0
	v_mov_b64_e32 v[66:67], 0
	v_mov_b64_e32 v[68:69], 0
	v_mov_b64_e32 v[70:71], 0
	v_mov_b64_e32 v[72:73], 0
	v_mov_b64_e32 v[74:75], 0
	v_mov_b64_e32 v[76:77], 0
	v_mov_b64_e32 v[78:79], 0
	v_mov_b64_e32 v[80:81], 0
	v_mov_b64_e32 v[82:83], 0
	v_mov_b64_e32 v[84:85], 0
	v_mov_b64_e32 v[86:87], 0
	v_mov_b64_e32 v[88:89], 0
	v_mov_b64_e32 v[90:91], 0
	v_mov_b64_e32 v[92:93], 0
	v_mov_b64_e32 v[94:95], 0
	v_mov_b64_e32 v[96:97], 0
	v_mov_b64_e32 v[98:99], 0
	v_mov_b64_e32 v[100:101], 0
	v_mov_b64_e32 v[102:103], 0
	v_mov_b64_e32 v[104:105], 0
	v_mov_b64_e32 v[106:107], 0
	v_mov_b64_e32 v[108:109], 0
	v_mov_b64_e32 v[110:111], 0
	v_mov_b64_e32 v[112:113], 0
	v_mov_b64_e32 v[114:115], 0
	v_mov_b64_e32 v[116:117], 0
	v_mov_b64_e32 v[118:119], 0
	v_mov_b64_e32 v[120:121], 0
	v_mov_b64_e32 v[122:123], 0
	v_mov_b64_e32 v[124:125], 0
	v_mov_b64_e32 v[126:127], 0
	s_addc_u32 s52, s29, 0
	s_mov_b32 s53, -2
	s_waitcnt lgkmcnt(0)
	.p2align	6

;     __device__ bool next(int i, pg8::Unit& u) const { const int cnt = (nwg - c + G - 1) / G; if (i >= reps * cnt) return false; return pg8::StaticOrder::next(i % cnt, u); }
; template <class Epi, class Sched, bool ALIGN_EPI = false, bool SP2 = false>
; __device__ __forceinline__ void gemm_phase(PG8_LAS unsigned char* lds, const Gemm g, const Sched& S, const Epi& E) {
;     ...
;         const bool has_next = S.next(ui + 1, nxt);
;         const char* nA = has_next ? (const char*)g.A + (size_t)nxt.pm * tstep : cA; const char* nB = has_next ? (const char*)g.Bt + (size_t)nxt.pn * tstep : cB;
;         for (int t = 0; t < nt; t += 2) {
;             const bool last = (t == nt - 2);
;             const char* a1 = cA + (size_t)(t + 1) * kstep;
;             const char* a2 = last ? nA : cA + (size_t)(t + 2) * kstep; const char* b2 = last ? nB : cB + (size_t)(t + 2) * kstep;
;             const char* a3 = a2 + kstep; const char* b3 = b2 + kstep;
;     ...
; #pragma unroll
;         for (int a = 0; a < 2; ++a)
; #pragma unroll
;             for (int b = 0; b < 2; ++b)
; #pragma unroll
;                 for (int m = 0; m < 4; ++m)
; #pragma unroll
;                     for (int n = 0; n < 2; ++n) acc[a][b][m][n] = (f32x4){0.f, 0.f, 0.f, 0.f};
.LBB0_954:
	s_ashr_i32 s53, s52, 31
	s_lshl_b64 s[22:23], s[52:53], 20
	s_add_u32 s54, s74, s22
	s_addc_u32 s55, s75, s23
	s_and_b64 s[24:25], s[62:63], exec
	s_cselect_b32 s1, s55, s27
	s_cselect_b32 s5, s54, s26
	s_ashr_i32 s41, s40, 31
	s_lshl_b64 s[24:25], s[40:41], 20
	s_add_u32 s56, s94, s24
	s_addc_u32 s57, s95, s25
	s_and_b64 s[30:31], s[62:63], exec
	s_cselect_b32 s17, s57, s29
	s_cselect_b32 s19, s56, s28
	s_add_u32 s26, s26, 0x80080
	s_addc_u32 s27, s27, 0
	s_add_u32 s33, s28, 0x100
	v_mov_b64_e32 v[0:1], 0
	v_mov_b64_e32 v[2:3], 0
	v_mov_b64_e32 v[4:5], 0
	v_mov_b64_e32 v[6:7], 0
	v_mov_b64_e32 v[8:9], 0
	v_mov_b64_e32 v[10:11], 0
	v_mov_b64_e32 v[12:13], 0
	v_mov_b64_e32 v[14:15], 0
	v_mov_b64_e32 v[16:17], 0
	v_mov_b64_e32 v[18:19], 0
	v_mov_b64_e32 v[20:21], 0
	v_mov_b64_e32 v[22:23], 0
	v_mov_b64_e32 v[24:25], 0
	v_mov_b64_e32 v[26:27], 0
	v_mov_b64_e32 v[28:29], 0
	v_mov_b64_e32 v[30:31], 0
	v_mov_b64_e32 v[32:33], 0
	v_mov_b64_e32 v[34:35], 0
	v_mov_b64_e32 v[36:37], 0
	v_mov_b64_e32 v[38:39], 0
	v_mov_b64_e32 v[40:41], 0
	v_mov_b64_e32 v[42:43], 0
	v_mov_b64_e32 v[44:45], 0
	v_mov_b64_e32 v[46:47], 0
	v_mov_b64_e32 v[48:49], 0
	v_mov_b64_e32 v[50:51], 0
	v_mov_b64_e32 v[52:53], 0
	v_mov_b64_e32 v[54:55], 0
	v_mov_b64_e32 v[56:57], 0
	v_mov_b64_e32 v[58:59], 0
	v_mov_b64_e32 v[60:61], 0
	v_mov_b64_e32 v[62:63], 0
	v_mov_b64_e32 v[64:65], 0
	v_mov_b64_e32 v[66:67], 0
	v_mov_b64_e32 v[68:69], 0
	v_mov_b64_e32 v[70:71], 0
	v_mov_b64_e32 v[72:73], 0
	v_mov_b64_e32 v[74:75], 0
	v_mov_b64_e32 v[76:77], 0
	v_mov_b64_e32 v[78:79], 0
	v_mov_b64_e32 v[80:81], 0
	v_mov_b64_e32 v[82:83], 0
	v_mov_b64_e32 v[84:85], 0
	v_mov_b64_e32 v[86:87], 0
	v_mov_b64_e32 v[88:89], 0
	v_mov_b64_e32 v[90:91], 0
	v_mov_b64_e32 v[92:93], 0
	v_mov_b64_e32 v[94:95], 0
	v_mov_b64_e32 v[96:97], 0
	v_mov_b64_e32 v[98:99], 0
	v_mov_b64_e32 v[100:101], 0
	v_mov_b64_e32 v[102:103], 0
	v_mov_b64_e32 v[104:105], 0
	v_mov_b64_e32 v[106:107], 0
	v_mov_b64_e32 v[108:109], 0
	v_mov_b64_e32 v[110:111], 0
	v_mov_b64_e32 v[112:113], 0
	v_mov_b64_e32 v[114:115], 0
	v_mov_b64_e32 v[116:117], 0
	v_mov_b64_e32 v[118:119], 0
	v_mov_b64_e32 v[120:121], 0
	v_mov_b64_e32 v[122:123], 0
	v_mov_b64_e32 v[124:125], 0
	v_mov_b64_e32 v[126:127], 0
	s_addc_u32 s44, s29, 0
	s_mov_b32 s45, -2
	s_waitcnt vmcnt(0)
	.p2align	6

;     __device__ bool next(int i, pg8::Unit& u) const { const int cnt = (nwg - c + G - 1) / G; if (i >= reps * cnt) return false; return pg8::StaticOrder::next(i % cnt, u); }
; template <class Epi, class Sched, bool ALIGN_EPI = false, bool SP2 = false>
; __device__ __forceinline__ void gemm_phase(PG8_LAS unsigned char* lds, const Gemm g, const Sched& S, const Epi& E) {
;     ...
;         const bool has_next = S.next(ui + 1, nxt);
;         const char* nA = has_next ? (const char*)g.A + (size_t)nxt.pm * tstep : cA; const char* nB = has_next ? (const char*)g.Bt + (size_t)nxt.pn * tstep : cB;
;         for (int t = 0; t < nt; t += 2) {
;             const bool last = (t == nt - 2);
;             const char* a1 = cA + (size_t)(t + 1) * kstep;
;             const char* a2 = last ? nA : cA + (size_t)(t + 2) * kstep; const char* b2 = last ? nB : cB + (size_t)(t + 2) * kstep;
;             const char* a3 = a2 + kstep; const char* b3 = b2 + kstep;
;     ...
; #pragma unroll
;         for (int a = 0; a < 2; ++a)
; #pragma unroll
;             for (int b = 0; b < 2; ++b)
; #pragma unroll
;                 for (int m = 0; m < 4; ++m)
; #pragma unroll
;                     for (int n = 0; n < 2; ++n) acc[a][b][m][n] = (f32x4){0.f, 0.f, 0.f, 0.f};
.LBB0_1179:
	s_ashr_i32 s21, s20, 31
	s_lshl_b64 s[22:23], s[20:21], 20
	s_add_u32 s22, s56, s22
	s_addc_u32 s23, s57, s23
	s_and_b64 s[24:25], s[4:5], exec
	s_cselect_b32 s7, s23, s27
	s_cselect_b32 s21, s22, s26
	s_ashr_i32 s19, s18, 31
	s_lshl_b64 s[24:25], s[18:19], 20
	s_add_u32 s24, s68, s24
	s_addc_u32 s25, s69, s25
	s_and_b64 s[30:31], s[4:5], exec
	s_cselect_b32 s19, s25, s29
	s_cselect_b32 s46, s24, s28
	s_add_u32 s26, s26, 0x80080
	s_addc_u32 s27, s27, 0
	s_add_u32 s47, s28, 0x100
	v_mov_b64_e32 v[0:1], 0
	v_mov_b64_e32 v[2:3], 0
	v_mov_b64_e32 v[4:5], 0
	v_mov_b64_e32 v[6:7], 0
	v_mov_b64_e32 v[8:9], 0
	v_mov_b64_e32 v[10:11], 0
	v_mov_b64_e32 v[12:13], 0
	v_mov_b64_e32 v[14:15], 0
	v_mov_b64_e32 v[16:17], 0
	v_mov_b64_e32 v[18:19], 0
	v_mov_b64_e32 v[20:21], 0
	v_mov_b64_e32 v[22:23], 0
	v_mov_b64_e32 v[24:25], 0
	v_mov_b64_e32 v[26:27], 0
	v_mov_b64_e32 v[28:29], 0
	v_mov_b64_e32 v[30:31], 0
	v_mov_b64_e32 v[32:33], 0
	v_mov_b64_e32 v[34:35], 0
	v_mov_b64_e32 v[36:37], 0
	v_mov_b64_e32 v[38:39], 0
	v_mov_b64_e32 v[40:41], 0
	v_mov_b64_e32 v[42:43], 0
	v_mov_b64_e32 v[44:45], 0
	v_mov_b64_e32 v[46:47], 0
	v_mov_b64_e32 v[48:49], 0
	v_mov_b64_e32 v[50:51], 0
	v_mov_b64_e32 v[52:53], 0
	v_mov_b64_e32 v[54:55], 0
	v_mov_b64_e32 v[56:57], 0
	v_mov_b64_e32 v[58:59], 0
	v_mov_b64_e32 v[60:61], 0
	v_mov_b64_e32 v[62:63], 0
	v_mov_b64_e32 v[64:65], 0
	v_mov_b64_e32 v[66:67], 0
	v_mov_b64_e32 v[68:69], 0
	v_mov_b64_e32 v[70:71], 0
	v_mov_b64_e32 v[72:73], 0
	v_mov_b64_e32 v[74:75], 0
	v_mov_b64_e32 v[76:77], 0
	v_mov_b64_e32 v[78:79], 0
	v_mov_b64_e32 v[80:81], 0
	v_mov_b64_e32 v[82:83], 0
	v_mov_b64_e32 v[84:85], 0
	v_mov_b64_e32 v[86:87], 0
	v_mov_b64_e32 v[88:89], 0
	v_mov_b64_e32 v[90:91], 0
	v_mov_b64_e32 v[92:93], 0
	v_mov_b64_e32 v[94:95], 0
	v_mov_b64_e32 v[96:97], 0
	v_mov_b64_e32 v[98:99], 0
	v_mov_b64_e32 v[100:101], 0
	v_mov_b64_e32 v[102:103], 0
	v_mov_b64_e32 v[104:105], 0
	v_mov_b64_e32 v[106:107], 0
	v_mov_b64_e32 v[108:109], 0
	v_mov_b64_e32 v[110:111], 0
	v_mov_b64_e32 v[112:113], 0
	v_mov_b64_e32 v[114:115], 0
	v_mov_b64_e32 v[116:117], 0
	v_mov_b64_e32 v[118:119], 0
	v_mov_b64_e32 v[120:121], 0
	v_mov_b64_e32 v[122:123], 0
	v_mov_b64_e32 v[124:125], 0
	v_mov_b64_e32 v[126:127], 0
	s_addc_u32 s48, s29, 0
	s_mov_b32 s49, -2
	s_waitcnt lgkmcnt(0)
	.p2align	6

;     __device__ bool next(int i, pg8::Unit& u) const { const int cnt = (nwg - c + G - 1) / G; if (i >= reps * cnt) return false; return pg8::StaticOrder::next(i % cnt, u); }
; template <class Epi, class Sched, bool ALIGN_EPI = false, bool SP2 = false>
; __device__ __forceinline__ void gemm_phase(PG8_LAS unsigned char* lds, const Gemm g, const Sched& S, const Epi& E) {
;     ...
;         const bool has_next = S.next(ui + 1, nxt);
;         const char* nA = has_next ? (const char*)g.A + (size_t)nxt.pm * tstep : cA; const char* nB = has_next ? (const char*)g.Bt + (size_t)nxt.pn * tstep : cB;
;         for (int t = 0; t < nt; t += 2) {
;             const bool last = (t == nt - 2);
;             const char* a1 = cA + (size_t)(t + 1) * kstep;
;             const char* a2 = last ? nA : cA + (size_t)(t + 2) * kstep; const char* b2 = last ? nB : cB + (size_t)(t + 2) * kstep;
;             const char* a3 = a2 + kstep; const char* b3 = b2 + kstep;
;     ...
; #pragma unroll
;         for (int a = 0; a < 2; ++a)
; #pragma unroll
;             for (int b = 0; b < 2; ++b)
; #pragma unroll
;                 for (int m = 0; m < 4; ++m)
; #pragma unroll
;                     for (int n = 0; n < 2; ++n) acc[a][b][m][n] = (f32x4){0.f, 0.f, 0.f, 0.f};
.LBB0_1372:
	s_ashr_i32 s29, s28, 31
	s_lshl_b64 s[34:35], s[28:29], 20
	s_add_u32 s34, s74, s34
	s_addc_u32 s35, s75, s35
	s_and_b64 s[36:37], s[30:31], exec
	s_cselect_b32 s29, s35, s9
	s_cselect_b32 s39, s34, s8
	s_ashr_i32 s27, s26, 31
	s_lshl_b64 s[36:37], s[26:27], 20
	v_readlane_b32 s44, v254, 22
	v_readlane_b32 s45, v254, 23
	s_add_u32 s36, s44, s36
	s_addc_u32 s37, s45, s37
	s_and_b64 s[44:45], s[30:31], exec
	s_cselect_b32 s27, s37, s43
	s_cselect_b32 s41, s36, s42
	s_add_u32 s8, s8, 0x80080
	s_addc_u32 s9, s9, 0
	s_add_u32 s48, s42, 0x100
	v_mov_b64_e32 v[0:1], 0
	v_mov_b64_e32 v[2:3], 0
	v_mov_b64_e32 v[4:5], 0
	v_mov_b64_e32 v[6:7], 0
	v_mov_b64_e32 v[8:9], 0
	v_mov_b64_e32 v[10:11], 0
	v_mov_b64_e32 v[12:13], 0
	v_mov_b64_e32 v[14:15], 0
	v_mov_b64_e32 v[16:17], 0
	v_mov_b64_e32 v[18:19], 0
	v_mov_b64_e32 v[20:21], 0
	v_mov_b64_e32 v[22:23], 0
	v_mov_b64_e32 v[24:25], 0
	v_mov_b64_e32 v[26:27], 0
	v_mov_b64_e32 v[28:29], 0
	v_mov_b64_e32 v[30:31], 0
	v_mov_b64_e32 v[32:33], 0
	v_mov_b64_e32 v[34:35], 0
	v_mov_b64_e32 v[36:37], 0
	v_mov_b64_e32 v[38:39], 0
	v_mov_b64_e32 v[40:41], 0
	v_mov_b64_e32 v[42:43], 0
	v_mov_b64_e32 v[44:45], 0
	v_mov_b64_e32 v[46:47], 0
	v_mov_b64_e32 v[48:49], 0
	v_mov_b64_e32 v[50:51], 0
	v_mov_b64_e32 v[52:53], 0
	v_mov_b64_e32 v[54:55], 0
	v_mov_b64_e32 v[56:57], 0
	v_mov_b64_e32 v[58:59], 0
	v_mov_b64_e32 v[60:61], 0
	v_mov_b64_e32 v[62:63], 0
	v_mov_b64_e32 v[64:65], 0
	v_mov_b64_e32 v[66:67], 0
	v_mov_b64_e32 v[68:69], 0
	v_mov_b64_e32 v[70:71], 0
	v_mov_b64_e32 v[72:73], 0
	v_mov_b64_e32 v[74:75], 0
	v_mov_b64_e32 v[76:77], 0
	v_mov_b64_e32 v[78:79], 0
	v_mov_b64_e32 v[80:81], 0
	v_mov_b64_e32 v[82:83], 0
	v_mov_b64_e32 v[84:85], 0
	v_mov_b64_e32 v[86:87], 0
	v_mov_b64_e32 v[88:89], 0
	v_mov_b64_e32 v[90:91], 0
	v_mov_b64_e32 v[92:93], 0
	v_mov_b64_e32 v[94:95], 0
	v_mov_b64_e32 v[96:97], 0
	v_mov_b64_e32 v[98:99], 0
	v_mov_b64_e32 v[100:101], 0
	v_mov_b64_e32 v[102:103], 0
	v_mov_b64_e32 v[104:105], 0
	v_mov_b64_e32 v[106:107], 0
	v_mov_b64_e32 v[124:125], 0
	v_mov_b64_e32 v[126:127], 0
	v_mov_b64_e32 v[128:129], 0
	v_mov_b64_e32 v[130:131], 0
	v_mov_b64_e32 v[132:133], 0
	v_mov_b64_e32 v[134:135], 0
	v_mov_b64_e32 v[136:137], 0
	v_mov_b64_e32 v[138:139], 0
	v_mov_b64_e32 v[140:141], 0
	v_mov_b64_e32 v[142:143], 0
	s_addc_u32 s49, s43, 0
	s_mov_b32 s66, -2
	.p2align	6

;     __device__ bool next(int i, pg8::Unit& u) const { const int cnt = (nwg - c + G - 1) / G; if (i >= reps * cnt) return false; return pg8::StaticOrder::next(i % cnt, u); }
; template <class Epi, class Sched, bool ALIGN_EPI = false, bool SP2 = false>
; __device__ __forceinline__ void gemm_phase(PG8_LAS unsigned char* lds, const Gemm g, const Sched& S, const Epi& E) {
;     ...
;         const bool has_next = S.next(ui + 1, nxt);
;         const char* nA = has_next ? (const char*)g.A + (size_t)nxt.pm * tstep : cA; const char* nB = has_next ? (const char*)g.Bt + (size_t)nxt.pn * tstep : cB;
;         for (int t = 0; t < nt; t += 2) {
;             const bool last = (t == nt - 2);
;             const char* a1 = cA + (size_t)(t + 1) * kstep;
;             const char* a2 = last ? nA : cA + (size_t)(t + 2) * kstep; const char* b2 = last ? nB : cB + (size_t)(t + 2) * kstep;
;             const char* a3 = a2 + kstep; const char* b3 = b2 + kstep;
;     ...
; #pragma unroll
;         for (int a = 0; a < 2; ++a)
; #pragma unroll
;             for (int b = 0; b < 2; ++b)
; #pragma unroll
;                 for (int m = 0; m < 4; ++m)
; #pragma unroll
;                     for (int n = 0; n < 2; ++n) acc[a][b][m][n] = (f32x4){0.f, 0.f, 0.f, 0.f};
.LBB0_1548:
	s_ashr_i32 s13, s12, 31
	s_lshl_b64 s[14:15], s[12:13], 20
	s_add_u32 s14, s60, s14
	s_addc_u32 s15, s61, s15
	s_and_b64 s[16:17], s[0:1], exec
	s_cselect_b32 s13, s15, s21
	s_cselect_b32 s39, s14, s20
	s_ashr_i32 s11, s10, 31
	s_lshl_b64 s[16:17], s[10:11], 20
	s_add_u32 s16, s72, s16
	s_addc_u32 s17, s73, s17
	s_and_b64 s[24:25], s[0:1], exec
	s_cselect_b32 s11, s17, s23
	s_cselect_b32 s40, s16, s22
	s_add_u32 s20, s20, 0x80080
	s_addc_u32 s21, s21, 0
	s_add_u32 s41, s22, 0x100
	v_mov_b64_e32 v[0:1], 0
	v_mov_b64_e32 v[2:3], 0
	v_mov_b64_e32 v[4:5], 0
	v_mov_b64_e32 v[6:7], 0
	v_mov_b64_e32 v[8:9], 0
	v_mov_b64_e32 v[10:11], 0
	v_mov_b64_e32 v[12:13], 0
	v_mov_b64_e32 v[14:15], 0
	v_mov_b64_e32 v[16:17], 0
	v_mov_b64_e32 v[18:19], 0
	v_mov_b64_e32 v[20:21], 0
	v_mov_b64_e32 v[22:23], 0
	v_mov_b64_e32 v[24:25], 0
	v_mov_b64_e32 v[26:27], 0
	v_mov_b64_e32 v[28:29], 0
	v_mov_b64_e32 v[30:31], 0
	v_mov_b64_e32 v[32:33], 0
	v_mov_b64_e32 v[34:35], 0
	v_mov_b64_e32 v[36:37], 0
	v_mov_b64_e32 v[38:39], 0
	v_mov_b64_e32 v[40:41], 0
	v_mov_b64_e32 v[42:43], 0
	v_mov_b64_e32 v[44:45], 0
	v_mov_b64_e32 v[46:47], 0
	v_mov_b64_e32 v[48:49], 0
	v_mov_b64_e32 v[50:51], 0
	v_mov_b64_e32 v[52:53], 0
	v_mov_b64_e32 v[54:55], 0
	v_mov_b64_e32 v[56:57], 0
	v_mov_b64_e32 v[58:59], 0
	v_mov_b64_e32 v[60:61], 0
	v_mov_b64_e32 v[62:63], 0
	v_mov_b64_e32 v[64:65], 0
	v_mov_b64_e32 v[66:67], 0
	v_mov_b64_e32 v[68:69], 0
	v_mov_b64_e32 v[70:71], 0
	v_mov_b64_e32 v[72:73], 0
	v_mov_b64_e32 v[74:75], 0
	v_mov_b64_e32 v[76:77], 0
	v_mov_b64_e32 v[78:79], 0
	v_mov_b64_e32 v[80:81], 0
	v_mov_b64_e32 v[82:83], 0
	v_mov_b64_e32 v[84:85], 0
	v_mov_b64_e32 v[86:87], 0
	v_mov_b64_e32 v[88:89], 0
	v_mov_b64_e32 v[90:91], 0
	v_mov_b64_e32 v[92:93], 0
	v_mov_b64_e32 v[94:95], 0
	v_mov_b64_e32 v[96:97], 0
	v_mov_b64_e32 v[98:99], 0
	v_mov_b64_e32 v[100:101], 0
	v_mov_b64_e32 v[102:103], 0
	v_mov_b64_e32 v[104:105], 0
	v_mov_b64_e32 v[106:107], 0
	v_mov_b64_e32 v[108:109], 0
	v_mov_b64_e32 v[110:111], 0
	v_mov_b64_e32 v[112:113], 0
	v_mov_b64_e32 v[114:115], 0
	v_mov_b64_e32 v[116:117], 0
	v_mov_b64_e32 v[118:119], 0
	v_mov_b64_e32 v[120:121], 0
	v_mov_b64_e32 v[122:123], 0
	v_mov_b64_e32 v[124:125], 0
	v_mov_b64_e32 v[126:127], 0
	s_addc_u32 s42, s23, 0
	s_mov_b32 s43, -2
	.p2align	6
